# DSA row-norm phase: gains loaded once, row pieces loaded together, next row prefetched
# speedup vs baseline: 1.0066x; 1.0066x over previous
.LBB0_1306:
	s_cmp_lt_i32 s62, 14
	s_cselect_b64 s[6:7], -1, 0
	s_cmp_gt_i32 s61, 13
	s_cselect_b64 s[8:9], -1, 0
	s_and_b64 s[6:7], s[6:7], s[8:9]
	s_mov_b64 s[12:13], 0
	s_andn2_b64 vcc, exec, s[6:7]
	s_mov_b64 s[16:17], 0
	s_cbranch_vccnz .LBB0_1366
	v_lshrrev_b32_e32 v0, 6, v192
	v_lshl_add_u32 v0, s2, 3, v0
	s_mov_b32 s3, 0x8000
	s_mov_b64 s[6:7], s[0:1]
	s_mov_b64 s[16:17], s[0:1]
	s_mov_b64 s[26:27], s[0:1]
	s_mov_b64 s[28:29], s[0:1]
	s_mov_b64 s[30:31], s[0:1]
	s_mov_b64 s[8:9], s[0:1]
	s_mov_b64 s[24:25], s[0:1]
	s_mov_b64 s[34:35], s[0:1]
	s_mov_b64 s[36:37], s[0:1]
	v_cmp_gt_i32_e32 vcc, s3, v0
	s_and_saveexec_b64 s[14:15], vcc
	s_cbranch_execz .LBB0_1312
	s_load_dwordx2 s[38:39], s[6:7], 0x100
	s_load_dwordx2 s[40:41], s[16:17], 0x100
	s_load_dwordx2 s[42:43], s[26:27], 0x100
	s_load_dwordx2 s[44:45], s[28:29], 0x100
	s_nop 0
	s_load_dwordx2 s[6:7], s[30:31], 0x100
	s_waitcnt lgkmcnt(0)
	s_add_u32 s16, s38, 0xc000000
	s_addc_u32 s17, s39, 0
	s_load_dwordx2 s[26:27], s[8:9], 0x90
	s_load_dwordx2 s[28:29], s[24:25], 0xa8
	s_load_dwordx2 s[30:31], s[34:35], 0xd0
	s_load_dwordx2 s[38:39], s[36:37], 0xd8
	v_and_b32_e32 v24, 63, v192
	v_mov_b32_e32 v3, 0
	v_lshlrev_b32_e32 v8, 3, v24
	v_mov_b32_e32 v9, v3
	v_lshlrev_b32_e32 v2, 2, v24
	v_lshl_add_u64 v[6:7], s[40:41], 0, v[8:9]
	s_mov_b64 s[8:9], 0x14000000
	v_lshlrev_b32_e32 v4, 4, v24
	v_mov_b32_e32 v5, v3
	v_lshl_add_u64 v[6:7], v[6:7], 0, s[8:9]
	v_lshlrev_b32_e32 v22, 1, v24
	v_mov_b32_e32 v23, v3
	v_lshl_add_u64 v[10:11], s[42:43], 0, v[2:3]
	s_mov_b64 s[8:9], 0x15000000
	s_waitcnt lgkmcnt(0)
	v_lshl_add_u64 v[4:5], s[26:27], 0, v[4:5]
	v_lshl_add_u64 v[10:11], v[10:11], 0, s[8:9]
	v_lshl_add_u64 v[16:17], s[44:45], 0, v[22:23]
	s_mov_b64 s[8:9], 0x15800000
	v_lshl_add_u64 v[18:19], s[6:7], 0, v[2:3]
	s_mov_b64 s[6:7], 0x15c00000
	s_mov_b32 s26, 0x3c800000
	v_lshl_add_u64 v[8:9], s[28:29], 0, v[8:9]
	v_lshl_add_u64 v[12:13], s[30:31], 0, v[2:3]
	v_lshl_add_u64 v[14:15], s[38:39], 0, v[2:3]
	v_lshl_add_u64 v[16:17], v[16:17], 0, s[8:9]
	v_cmp_gt_u32_e32 vcc, 16, v24
	v_lshl_add_u64 v[18:19], v[18:19], 0, s[6:7]
	s_lshl_b32 s3, s22, 3
	s_mov_b64 s[24:25], 0
	v_lshlrev_b32_e32 v2, 2, v2
	v_mov_b32_e32 v20, 0x358637bd
	s_mov_b32 s28, 0x800000
	v_lshlrev_b32_e32 v22, 2, v22
	v_lshlrev_b32_e32 v24, 2, v24
	v_mov_b32_e32 v25, v3
	s_brev_b32 s27, 60
	s_movk_i32 s29, 0x7fff
	global_load_dwordx4 v[44:47], v[4:5], off
	global_load_dwordx2 v[48:49], v[8:9], off
	global_load_dword v50, v[12:13], off
	global_load_dword v51, v[14:15], off
	v_ashrrev_i32_e32 v1, 31, v0
	v_lshlrev_b64 v[26:27], 11, v[0:1]
	v_lshl_add_u64 v[26:27], s[16:17], 0, v[26:27]
	v_lshl_add_u64 v[36:37], v[26:27], 0, v[2:3]
	v_lshl_add_u64 v[38:39], v[26:27], 0, v[22:23]
	v_lshl_add_u64 v[26:27], v[26:27], 0, v[24:25]
	global_load_dwordx4 v[56:59], v[36:37], off
	global_load_dwordx2 v[60:61], v[38:39], off offset:1024
	global_load_dword v62, v[26:27], off offset:1536
	global_load_dword v63, v[26:27], off offset:1792
	s_waitcnt vmcnt(0)
	s_branch .LBB0_1310

.LBB0_1310:
	s_waitcnt vmcnt(4)
	v_mov_b32_e32 v28, v56
	v_mov_b32_e32 v29, v57
	v_mov_b32_e32 v30, v58
	v_mov_b32_e32 v31, v59
	v_mov_b32_e32 v52, v60
	v_mov_b32_e32 v53, v61
	v_mov_b32_e32 v54, v62
	v_mov_b32_e32 v55, v63
	v_add_u32_e32 v42, s3, v0
	v_min_u32_e32 v42, s29, v42
	v_mov_b32_e32 v43, 0
	v_lshlrev_b64 v[64:65], 11, v[42:43]
	v_lshl_add_u64 v[64:65], s[16:17], 0, v[64:65]
	v_lshl_add_u64 v[66:67], v[64:65], 0, v[2:3]
	global_load_dwordx4 v[56:59], v[66:67], off
	v_lshl_add_u64 v[66:67], v[64:65], 0, v[22:23]
	global_load_dwordx2 v[60:61], v[66:67], off offset:1024
	v_lshl_add_u64 v[64:65], v[64:65], 0, v[24:25]
	global_load_dword v62, v[64:65], off offset:1536
	global_load_dword v63, v[64:65], off offset:1792
	v_ashrrev_i32_e32 v1, 31, v0
	v_lshlrev_b64 v[36:37], 9, v[0:1]
	v_lshl_add_u64 v[36:37], v[6:7], 0, v[36:37]
	v_mul_f32_e32 v21, v29, v29
	v_mul_f32_e32 v38, v31, v31
	v_fmac_f32_e32 v21, v28, v28
	v_fmac_f32_e32 v38, v30, v30
	v_add_f32_e32 v21, v21, v38
	s_nop 1
	v_add_f32_dpp v21, v21, v21 quad_perm:[1,0,3,2] row_mask:0xf bank_mask:0xf bound_ctrl:1
	s_nop 1
	v_add_f32_dpp v21, v21, v21 quad_perm:[2,3,0,1] row_mask:0xf bank_mask:0xf bound_ctrl:1
	s_nop 1
	v_add_f32_dpp v21, v21, v21 row_half_mirror row_mask:0xf bank_mask:0xf bound_ctrl:1
	s_nop 1
	v_add_f32_dpp v21, v21, v21 row_mirror row_mask:0xf bank_mask:0xf bound_ctrl:1
	v_mov_b32_e32 v38, v21
	s_nop 1
	v_permlane16_swap_b32_e32 v21, v38
	v_add_f32_e32 v21, v21, v38
	v_mov_b32_e32 v38, v21
	s_nop 1
	v_permlane32_swap_b32_e32 v21, v38
	v_add_f32_e32 v21, v21, v38
	v_fmamk_f32 v21, v21, 0x3b800000, v20
	v_mul_f32_e32 v38, 0x4b800000, v21
	v_cmp_gt_f32_e64 s[6:7], s28, v21
	s_nop 1
	v_cndmask_b32_e64 v21, v21, v38, s[6:7]
	v_rsq_f32_e32 v21, v21
	v_mul_f32_e32 v40, 0x45800000, v21
	v_cndmask_b32_e64 v40, v21, v40, s[6:7]
	v_mov_b32_e32 v21, v54
	v_pk_mul_f32 v[28:29], v[28:29], v[40:41] op_sel_hi:[1,0]
	v_pk_mul_f32 v[30:31], v[30:31], v[40:41] op_sel_hi:[1,0]
	v_pk_mul_f32 v[28:29], v[44:45], v[28:29]
	v_pk_mul_f32 v[30:31], v[46:47], v[30:31]
	v_cvt_pk_bf16_f32 v28, v28, v29
	v_cvt_pk_bf16_f32 v29, v30, v31
	global_store_dwordx2 v[36:37], v[28:29], off
	v_lshlrev_b64 v[32:33], 8, v[0:1]
	v_lshlrev_b64 v[34:35], 7, v[0:1]
	v_lshl_add_u64 v[32:33], v[10:11], 0, v[32:33]
	v_lshl_add_u64 v[34:35], v[16:17], 0, v[34:35]
	v_pk_mul_f32 v[36:37], v[52:53], v[52:53]
	v_add_f32_dpp v38, v21, v21 quad_perm:[1,0,3,2] row_mask:0xf bank_mask:0xf bound_ctrl:1
	v_add_f32_e32 v36, v36, v37
	s_nop 0
	v_add_f32_dpp v37, v38, v38 quad_perm:[2,3,0,1] row_mask:0xf bank_mask:0xf bound_ctrl:1
	v_add_f32_dpp v36, v36, v36 quad_perm:[1,0,3,2] row_mask:0xf bank_mask:0xf bound_ctrl:1
	s_nop 0
	v_add_f32_dpp v37, v37, v37 row_half_mirror row_mask:0xf bank_mask:0xf bound_ctrl:1
	v_add_f32_dpp v36, v36, v36 quad_perm:[2,3,0,1] row_mask:0xf bank_mask:0xf bound_ctrl:1
	s_nop 0
	v_add_f32_dpp v37, v37, v37 row_mirror row_mask:0xf bank_mask:0xf bound_ctrl:1
	v_mov_b32_e32 v38, v37
	v_add_f32_dpp v36, v36, v36 row_half_mirror row_mask:0xf bank_mask:0xf bound_ctrl:1
	s_nop 0
	v_permlane16_swap_b32_e32 v37, v38
	v_add_f32_dpp v36, v36, v36 row_mirror row_mask:0xf bank_mask:0xf bound_ctrl:1
	v_add_f32_e32 v38, v37, v38
	v_mov_b32_e32 v39, v36
	v_mov_b32_e32 v42, v38
	s_nop 0
	v_permlane16_swap_b32_e32 v36, v39
	v_permlane32_swap_b32_e32 v38, v42
	v_add_f32_e32 v37, v36, v39
	v_add_f32_e32 v36, v38, v42
	v_fmac_f32_e32 v21, 0xbc800000, v36
	v_mul_f32_e32 v36, v21, v21
	v_mov_b32_e32 v39, v37
	s_nop 1
	v_permlane32_swap_b32_e32 v37, v39
	v_mov_b32_dpp v36, v36 quad_perm:[1,0,3,2] row_mask:0xf bank_mask:0xf bound_ctrl:1
	v_fmac_f32_e32 v36, v21, v21
	s_nop 1
	v_add_f32_dpp v36, v36, v36 quad_perm:[2,3,0,1] row_mask:0xf bank_mask:0xf bound_ctrl:1
	s_nop 1
	v_add_f32_dpp v36, v36, v36 row_half_mirror row_mask:0xf bank_mask:0xf bound_ctrl:1
	s_nop 1
	v_add_f32_dpp v36, v36, v36 row_mirror row_mask:0xf bank_mask:0xf bound_ctrl:1
	v_mov_b32_e32 v38, v36
	s_nop 1
	v_permlane16_swap_b32_e32 v36, v38
	v_add_f32_e32 v36, v36, v38
	v_mov_b32_e32 v38, v36
	s_nop 1
	v_permlane32_swap_b32_e32 v36, v38
	v_pk_add_f32 v[36:37], v[36:37], v[38:39]
	s_nop 0
	v_pk_fma_f32 v[36:37], v[36:37], s[26:27], v[20:21] op_sel_hi:[1,1,0]
	s_nop 0
	v_mul_f32_e32 v38, 0x4b800000, v37
	v_mul_f32_e32 v39, 0x4b800000, v36
	v_cmp_gt_f32_e64 s[6:7], s28, v37
	v_cmp_gt_f32_e64 s[8:9], s28, v36
	s_nop 0
	v_cndmask_b32_e64 v37, v37, v38, s[6:7]
	v_cndmask_b32_e64 v36, v36, v39, s[8:9]
	v_rsq_f32_e32 v37, v37
	v_rsq_f32_e32 v38, v36
	v_mul_f32_e32 v36, 0x45800000, v37
	v_mul_f32_e32 v39, 0x45800000, v38
	v_cndmask_b32_e64 v36, v37, v36, s[6:7]
	v_cndmask_b32_e64 v37, v38, v39, s[8:9]
	v_pk_mul_f32 v[28:29], v[52:53], v[36:37] op_sel_hi:[1,0]
	v_mul_f32_e32 v21, v21, v37
	v_pk_mul_f32 v[28:29], v[48:49], v[28:29]
	v_fma_f32 v41, v50, v21, v51
	v_cvt_pk_bf16_f32 v21, v28, v29
	v_cvt_pk_bf16_f32 v28, v41, s0
	global_store_dword v[32:33], v21, off
	global_store_short v[34:35], v28, off
	s_and_saveexec_b64 s[6:7], vcc
	s_cbranch_execz .LBB0_1309
	v_lshlrev_b64 v[26:27], 6, v[0:1]
	v_lshl_add_u64 v[26:27], v[18:19], 0, v[26:27]
	v_mul_f32_e32 v1, 0x3d000000, v55
	global_store_dword v[26:27], v1, off
	s_branch .LBB0_1309
